# cross-attention: P.V fragment LDS reads prefetched 8 deep through a register ring (counted lgkmcnt) instead of one exposed round trip per MFMA
# baseline (speedup 1.0000x reference)
; __device__ __forceinline__ uint2 pack4(float a, float b, float c, float d) { uint2 r; r.x = pk2(a, b); r.y = pk2(c, d); return r; }
; template <int NC, int DQK, int DV, bool CAUSAL, bool PF> ...
;     ...
;         _Pragma("unroll") for (int m = 0; m < 4; ++m) _Pragma("unroll") for (int j = 0; j < 4; ++j) { float pv = __builtin_amdgcn_exp2f(s[m][j] - mm); s[m][j] = pv; psum += pv; }
;       } else {
;         float cc = bb - mrun[c];
;         _Pragma("unroll") for (int m = 0; m < 4; ++m) _Pragma("unroll") for (int j = 0; j < 4; ++j) { float pv = __builtin_amdgcn_exp2f(s[m][j] * scale_log2 + cc); s[m][j] = pv; psum += pv; }
;       }
;       lsum[c] += psum;
;       _Pragma("unroll") for (int k2 = 0; k2 < 2; ++k2) {
;         uint2 lo = pack4(s[2 * k2][0], s[2 * k2][1], s[2 * k2][2], s[2 * k2][3]);
;         uint2 hi = pack4(s[2 * k2 + 1][0], s[2 * k2 + 1][1], s[2 * k2 + 1][2], s[2 * k2 + 1][3]);
;         uint4 pk; pk.x = lo.x; pk.y = lo.y; pk.z = hi.x; pk.w = hi.y;
;         pf[c][k2] = *(bf16x8*)&pk;
;       }
;     }
;     _Pragma("unroll") for (int k2 = 0; k2 < 2; ++k2) _Pragma("unroll") for (int v = 0; v < NVT; ++v) {
;       bf16x8 a = *(const bf16x8*)&Vb[(16 * v + fr) * VLD + 32 * k2 + fq * 8];
;       _Pragma("unroll") for (int c = 0; c < NC; ++c) O[c][v] = __builtin_amdgcn_mfma_f32_16x16x32_bf16(a, pf[c][k2], O[c][v], 0, 0, 0);
;       if ((v & 3) == 3) __builtin_amdgcn_sched_barrier(0);
;     }
.LBB0_2080:
	v_fmamk_f32 v78, v78, 0x3db8aa3b, v191
	v_exp_f32_e32 v78, v78
	v_fmamk_f32 v79, v79, 0x3db8aa3b, v191
	v_exp_f32_e32 v79, v79
	v_fmamk_f32 v80, v80, 0x3db8aa3b, v191
	v_exp_f32_e32 v80, v80
	v_fmamk_f32 v81, v81, 0x3db8aa3b, v191
	v_exp_f32_e32 v81, v81
	v_fmamk_f32 v74, v74, 0x3db8aa3b, v191
	v_add_f32_e32 v82, 0, v78
	v_exp_f32_e32 v74, v74
	v_fmamk_f32 v75, v75, 0x3db8aa3b, v191
	v_add_f32_e32 v82, v79, v82
	v_exp_f32_e32 v75, v75
	v_fmamk_f32 v76, v76, 0x3db8aa3b, v191
	v_add_f32_e32 v82, v80, v82
	v_exp_f32_e32 v76, v76
	v_fmamk_f32 v77, v77, 0x3db8aa3b, v191
	v_add_f32_e32 v82, v81, v82
	v_exp_f32_e32 v77, v77
	v_fmamk_f32 v70, v70, 0x3db8aa3b, v191
	v_add_f32_e32 v82, v74, v82
	v_exp_f32_e32 v83, v70
	v_add_f32_e32 v82, v75, v82
	v_add_f32_e32 v82, v76, v82
	v_add_f32_e32 v82, v77, v82
	v_fmamk_f32 v71, v71, 0x3db8aa3b, v191
	v_readlane_b32 s8, v254, 40
	v_add_f32_e32 v70, v83, v82
	v_exp_f32_e32 v82, v71
	v_fmamk_f32 v71, v72, 0x3db8aa3b, v191
	v_add3_u32 v32, s8, v32, v151
	v_exp_f32_e32 v84, v71
	v_fmamk_f32 v71, v73, 0x3db8aa3b, v191
	v_cvt_pk_bf16_f32 v72, v74, v75
	v_cvt_pk_bf16_f32 v73, v76, v77
	ds_read_b128 v[216:219], v32
	ds_read_b128 v[220:223], v32 offset:2304
	ds_read_b128 v[224:227], v32 offset:4608
	ds_read_b128 v[228:231], v32 offset:6912
	ds_read_b128 v[232:235], v32 offset:9216
	ds_read_b128 v[236:239], v32 offset:11520
	ds_read_b128 v[240:243], v32 offset:13824
	ds_read_b128 v[244:247], v32 offset:16128
	v_exp_f32_e32 v85, v71
	v_fmamk_f32 v66, v66, 0x3db8aa3b, v191
	v_exp_f32_e32 v86, v66
	v_add_f32_e32 v70, v82, v70
	v_add_f32_e32 v70, v84, v70
	v_add_f32_e32 v70, v85, v70
	v_add_f32_e32 v66, v86, v70
	v_cvt_pk_bf16_f32 v70, v78, v79
	v_cvt_pk_bf16_f32 v71, v80, v81
	v_fmamk_f32 v67, v67, 0x3db8aa3b, v191
	v_exp_f32_e32 v87, v67
	s_waitcnt lgkmcnt(7)
	v_mfma_f32_16x16x32_bf16 v[62:65], v[216:219], v[70:73], v[62:65]
	ds_read_b128 v[216:219], v32 offset:18432
	v_fmamk_f32 v67, v68, 0x3db8aa3b, v191
	v_exp_f32_e32 v88, v67
	s_waitcnt lgkmcnt(7)
	v_mfma_f32_16x16x32_bf16 v[58:61], v[220:223], v[70:73], v[58:61]
	ds_read_b128 v[220:223], v32 offset:20736
	v_fmac_f32_e32 v191, 0x3db8aa3b, v69
	v_exp_f32_e32 v69, v191
	s_waitcnt lgkmcnt(7)
	v_mfma_f32_16x16x32_bf16 v[54:57], v[224:227], v[70:73], v[54:57]
	ds_read_b128 v[224:227], v32 offset:23040
	s_lshl_b64 s[0:1], s[0:1], 1
	v_add_f32_e32 v66, v87, v66
	s_add_u32 s0, s12, s0
	v_add_f32_e32 v66, v88, v66
	s_addc_u32 s1, s13, s1
	v_add_f32_e32 v89, v69, v66
	v_cvt_pk_bf16_f32 v66, v83, v82
	v_cvt_pk_bf16_f32 v67, v84, v85
	v_cvt_pk_bf16_f32 v68, v86, v87
	v_cvt_pk_bf16_f32 v69, v88, v69
	s_waitcnt lgkmcnt(7)
	v_mfma_f32_16x16x32_bf16 v[50:53], v[228:231], v[70:73], v[50:53]
	ds_read_b128 v[228:231], v32 offset:25344
	s_waitcnt lgkmcnt(7)
	v_mfma_f32_16x16x32_bf16 v[46:49], v[232:235], v[70:73], v[46:49]
	ds_read_b128 v[232:235], v32 offset:27648
	s_waitcnt lgkmcnt(7)
	v_mfma_f32_16x16x32_bf16 v[38:41], v[236:239], v[70:73], v[38:41]
	ds_read_b128 v[236:239], v32 offset:29952
	s_waitcnt lgkmcnt(7)
	v_mfma_f32_16x16x32_bf16 v[42:45], v[240:243], v[70:73], v[42:45]
	ds_read_b128 v[240:243], v32 offset:32256
	s_waitcnt lgkmcnt(7)
	v_mfma_f32_16x16x32_bf16 v[34:37], v[244:247], v[70:73], v[34:37]
	ds_read_b128 v[244:247], v32 offset:34560
	s_waitcnt lgkmcnt(7)
	v_mfma_f32_16x16x32_bf16 v[28:31], v[216:219], v[70:73], v[28:31]
	s_waitcnt lgkmcnt(6)
	v_mfma_f32_16x16x32_bf16 v[24:27], v[220:223], v[70:73], v[24:27]
	s_waitcnt lgkmcnt(5)
	v_mfma_f32_16x16x32_bf16 v[20:23], v[224:227], v[70:73], v[20:23]
	s_waitcnt lgkmcnt(4)
	v_mfma_f32_16x16x32_bf16 v[16:19], v[228:231], v[70:73], v[16:19]
	s_waitcnt lgkmcnt(3)
	v_mfma_f32_16x16x32_bf16 v[12:15], v[232:235], v[70:73], v[12:15]
	s_waitcnt lgkmcnt(2)
	v_mfma_f32_16x16x32_bf16 v[8:11], v[236:239], v[70:73], v[8:11]
	s_waitcnt lgkmcnt(1)
	v_mfma_f32_16x16x32_bf16 v[4:7], v[240:243], v[70:73], v[4:7]
	s_waitcnt lgkmcnt(0)
	v_mfma_f32_16x16x32_bf16 v[0:3], v[244:247], v[70:73], v[0:3]
	ds_read_b128 v[216:219], v32 offset:64
	ds_read_b128 v[220:223], v32 offset:2368
	ds_read_b128 v[224:227], v32 offset:4672
	ds_read_b128 v[228:231], v32 offset:6976
	ds_read_b128 v[232:235], v32 offset:9280
	ds_read_b128 v[236:239], v32 offset:11584
	ds_read_b128 v[240:243], v32 offset:13888
	ds_read_b128 v[244:247], v32 offset:16192
	s_waitcnt lgkmcnt(7)
	v_mfma_f32_16x16x32_bf16 v[62:65], v[216:219], v[66:69], v[62:65]
	ds_read_b128 v[216:219], v32 offset:18496
	s_waitcnt lgkmcnt(7)
	v_mfma_f32_16x16x32_bf16 v[58:61], v[220:223], v[66:69], v[58:61]
	ds_read_b128 v[220:223], v32 offset:20800
	s_waitcnt lgkmcnt(7)
	v_mfma_f32_16x16x32_bf16 v[54:57], v[224:227], v[66:69], v[54:57]
	ds_read_b128 v[224:227], v32 offset:23104
	s_waitcnt lgkmcnt(7)
	v_mfma_f32_16x16x32_bf16 v[50:53], v[228:231], v[66:69], v[50:53]
	ds_read_b128 v[228:231], v32 offset:25408
	s_waitcnt lgkmcnt(7)
	v_mfma_f32_16x16x32_bf16 v[46:49], v[232:235], v[66:69], v[46:49]
	ds_read_b128 v[232:235], v32 offset:27712
	s_waitcnt lgkmcnt(7)
	v_mfma_f32_16x16x32_bf16 v[38:41], v[236:239], v[66:69], v[38:41]
	ds_read_b128 v[236:239], v32 offset:30016
	s_waitcnt lgkmcnt(7)
	v_mfma_f32_16x16x32_bf16 v[42:45], v[240:243], v[66:69], v[42:45]
	ds_read_b128 v[240:243], v32 offset:32320
	s_waitcnt lgkmcnt(7)
	v_mfma_f32_16x16x32_bf16 v[34:37], v[244:247], v[66:69], v[34:37]
	ds_read_b128 v[244:247], v32 offset:34624
	s_waitcnt lgkmcnt(7)
; __device__ __forceinline__ uint2 pack4(float a, float b, float c, float d) { uint2 r; r.x = pk2(a, b); r.y = pk2(c, d); return r; }
; template <int NC, int DQK, int DV, bool CAUSAL, bool PF> ...
;     ...
;     _Pragma("unroll") for (int k2 = 0; k2 < 2; ++k2) _Pragma("unroll") for (int v = 0; v < NVT; ++v) {
;       bf16x8 a = *(const bf16x8*)&Vb[(16 * v + fr) * VLD + 32 * k2 + fq * 8];
;       _Pragma("unroll") for (int c = 0; c < NC; ++c) O[c][v] = __builtin_amdgcn_mfma_f32_16x16x32_bf16(a, pf[c][k2], O[c][v], 0, 0, 0);
;       if ((v & 3) == 3) __builtin_amdgcn_sched_barrier(0);
;     }
;   }
;   float inv[NC];
;   _Pragma("unroll") for (int c = 0; c < NC; ++c) { float l = lsum[c]; l += sx<16>(l, lane); l += sx<32>(l, lane); inv[c] = 1.f / l; }
;   u16* orow = Og + (long)(wid * 16 + fr) * o_stride;
;   if (NC == 2) {
;     float ss = 0.f;
;     _Pragma("unroll") for (int v = 0; v < NVT; ++v) _Pragma("unroll") for (int j = 0; j < 4; ++j) { float o = O[0][v][j] * inv[0] - lam * O[NC - 1][v][j] * inv[NC - 1]; O[0][v][j] = o; ss += o * o; }
;     ss += sx<16>(ss, lane); ss += sx<32>(ss, lane);
;     float rs = rsqrtf(ss * (1.f / DV) + EPS) * outscale;
;     _Pragma("unroll") for (int v = 0; v < NVT; ++v) {
;       float4 g = *(const float4*)&subln_g[16 * v + fq * 4];
;       *(uint2*)&orow[16 * v + fq * 4] = pack4(O[0][v][0] * rs * g.x, O[0][v][1] * rs * g.y, O[0][v][2] * rs * g.z, O[0][v][3] * rs * g.w);
;     }
;   } else {
;     _Pragma("unroll") for (int v = 0; v < NVT; ++v)
;       *(uint2*)&orow[16 * v + fq * 4] = pack4(O[0][v][0] * inv[0], O[0][v][1] * inv[0], O[0][v][2] * inv[0], O[0][v][3] * inv[0]);
	v_mfma_f32_16x16x32_bf16 v[28:31], v[216:219], v[66:69], v[28:31]
	s_waitcnt lgkmcnt(6)
	v_mfma_f32_16x16x32_bf16 v[24:27], v[220:223], v[66:69], v[24:27]
	s_waitcnt lgkmcnt(5)
	v_mfma_f32_16x16x32_bf16 v[20:23], v[224:227], v[66:69], v[20:23]
	s_waitcnt lgkmcnt(4)
	v_mfma_f32_16x16x32_bf16 v[16:19], v[228:231], v[66:69], v[16:19]
	s_waitcnt lgkmcnt(3)
	v_mfma_f32_16x16x32_bf16 v[12:15], v[232:235], v[66:69], v[12:15]
	s_waitcnt lgkmcnt(2)
	v_mfma_f32_16x16x32_bf16 v[8:11], v[236:239], v[66:69], v[8:11]
	s_waitcnt lgkmcnt(1)
	v_mfma_f32_16x16x32_bf16 v[4:7], v[240:243], v[66:69], v[4:7]
	s_waitcnt lgkmcnt(0)
	v_mfma_f32_16x16x32_bf16 v[0:3], v[244:247], v[66:69], v[0:3]
	v_add_f32_e32 v32, v150, v89
	ds_swizzle_b32 v66, v32 offset:swizzle(SWAP,16)
	s_lshl_b32 s8, s19, 1
	s_add_u32 s0, s0, s8
	s_addc_u32 s1, s1, 0
	s_add_i32 s18, s18, s70
	s_waitcnt lgkmcnt(0)
	v_add_f32_e32 v66, v32, v66
	ds_bpermute_b32 v67, v149, v66
	v_lshlrev_b32_e32 v32, 3, v148
	s_cmpk_lt_i32 s18, 0x400
	s_waitcnt lgkmcnt(0)
	v_add_f32_e32 v68, v66, v67
	v_div_scale_f32 v69, s[8:9], v68, v68, 1.0
	v_rcp_f32_e32 v70, v69
	v_div_scale_f32 v71, vcc, 1.0, v68, 1.0
	v_lshl_add_u64 v[66:67], s[0:1], 0, v[146:147]
	v_fma_f32 v72, -v69, v70, 1.0
	v_fmac_f32_e32 v70, v72, v70
	v_mul_f32_e32 v72, v71, v70
	v_fma_f32 v73, -v69, v72, v71
	v_fmac_f32_e32 v72, v73, v70
	v_fma_f32 v69, -v69, v72, v71
	v_div_fmas_f32 v69, v69, v70, v72
	v_div_fixup_f32 v68, v69, v68, 1.0
	v_pk_mul_f32 v[62:63], v[62:63], v[68:69] op_sel_hi:[1,0]
	v_pk_mul_f32 v[64:65], v[64:65], v[68:69] op_sel_hi:[1,0]
	v_pk_mul_f32 v[38:39], v[38:39], v[68:69] op_sel_hi:[1,0]
	v_pk_mul_f32 v[40:41], v[40:41], v[68:69] op_sel_hi:[1,0]
	v_cvt_pk_bf16_f32 v62, v62, v63
	v_cvt_pk_bf16_f32 v63, v64, v65
	v_lshl_add_u64 v[64:65], v[66:67], 0, v[32:33]
	v_cvt_pk_bf16_f32 v38, v38, v39
	v_cvt_pk_bf16_f32 v39, v40, v41
	v_pk_mul_f32 v[58:59], v[58:59], v[68:69] op_sel_hi:[1,0]
	v_pk_mul_f32 v[60:61], v[60:61], v[68:69] op_sel_hi:[1,0]
	v_pk_mul_f32 v[54:55], v[54:55], v[68:69] op_sel_hi:[1,0]
	v_pk_mul_f32 v[56:57], v[56:57], v[68:69] op_sel_hi:[1,0]
	v_pk_mul_f32 v[50:51], v[50:51], v[68:69] op_sel_hi:[1,0]
	v_pk_mul_f32 v[52:53], v[52:53], v[68:69] op_sel_hi:[1,0]
	v_pk_mul_f32 v[46:47], v[46:47], v[68:69] op_sel_hi:[1,0]
	v_pk_mul_f32 v[48:49], v[48:49], v[68:69] op_sel_hi:[1,0]
	global_store_dwordx2 v[64:65], v[38:39], off offset:160
	v_pk_mul_f32 v[38:39], v[42:43], v[68:69] op_sel_hi:[1,0]
	v_pk_mul_f32 v[40:41], v[44:45], v[68:69] op_sel_hi:[1,0]
	v_pk_mul_f32 v[34:35], v[34:35], v[68:69] op_sel_hi:[1,0]
	v_pk_mul_f32 v[36:37], v[36:37], v[68:69] op_sel_hi:[1,0]
	v_pk_mul_f32 v[28:29], v[28:29], v[68:69] op_sel_hi:[1,0]
	v_pk_mul_f32 v[30:31], v[30:31], v[68:69] op_sel_hi:[1,0]
	v_pk_mul_f32 v[24:25], v[24:25], v[68:69] op_sel_hi:[1,0]
	v_pk_mul_f32 v[26:27], v[26:27], v[68:69] op_sel_hi:[1,0]
	v_pk_mul_f32 v[20:21], v[20:21], v[68:69] op_sel_hi:[1,0]
	v_pk_mul_f32 v[22:23], v[22:23], v[68:69] op_sel_hi:[1,0]
	v_pk_mul_f32 v[16:17], v[16:17], v[68:69] op_sel_hi:[1,0]
	v_pk_mul_f32 v[18:19], v[18:19], v[68:69] op_sel_hi:[1,0]
	v_pk_mul_f32 v[12:13], v[12:13], v[68:69] op_sel_hi:[1,0]
	v_pk_mul_f32 v[14:15], v[14:15], v[68:69] op_sel_hi:[1,0]
	v_pk_mul_f32 v[8:9], v[8:9], v[68:69] op_sel_hi:[1,0]
	v_pk_mul_f32 v[10:11], v[10:11], v[68:69] op_sel_hi:[1,0]
	v_pk_mul_f32 v[4:5], v[4:5], v[68:69] op_sel_hi:[1,0]
	v_pk_mul_f32 v[6:7], v[6:7], v[68:69] op_sel_hi:[1,0]
	v_pk_mul_f32 v[0:1], v[0:1], v[68:69] op_sel_hi:[1,0]
	v_pk_mul_f32 v[2:3], v[2:3], v[68:69] op_sel_hi:[1,0]
	v_cvt_pk_bf16_f32 v58, v58, v59
	v_cvt_pk_bf16_f32 v59, v60, v61
	v_cvt_pk_bf16_f32 v54, v54, v55
	v_cvt_pk_bf16_f32 v55, v56, v57
	v_cvt_pk_bf16_f32 v50, v50, v51
	v_cvt_pk_bf16_f32 v51, v52, v53
	v_cvt_pk_bf16_f32 v46, v46, v47
	v_cvt_pk_bf16_f32 v47, v48, v49
	v_cvt_pk_bf16_f32 v38, v38, v39
	v_cvt_pk_bf16_f32 v39, v40, v41
	v_cvt_pk_bf16_f32 v34, v34, v35
	v_cvt_pk_bf16_f32 v35, v36, v37
	v_cvt_pk_bf16_f32 v28, v28, v29
	v_cvt_pk_bf16_f32 v29, v30, v31
	v_cvt_pk_bf16_f32 v24, v24, v25
	v_cvt_pk_bf16_f32 v25, v26, v27
	v_cvt_pk_bf16_f32 v20, v20, v21
	v_cvt_pk_bf16_f32 v21, v22, v23
	v_cvt_pk_bf16_f32 v16, v16, v17
	v_cvt_pk_bf16_f32 v17, v18, v19
	v_cvt_pk_bf16_f32 v12, v12, v13
	v_cvt_pk_bf16_f32 v13, v14, v15
	v_cvt_pk_bf16_f32 v8, v8, v9
	v_cvt_pk_bf16_f32 v9, v10, v11
	v_cvt_pk_bf16_f32 v4, v4, v5
	v_cvt_pk_bf16_f32 v5, v6, v7
	v_cvt_pk_bf16_f32 v0, v0, v1
	v_cvt_pk_bf16_f32 v1, v2, v3
	global_store_dwordx2 v[64:65], v[62:63], off
	global_store_dwordx2 v[64:65], v[58:59], off offset:32
	global_store_dwordx2 v[64:65], v[54:55], off offset:64
	global_store_dwordx2 v[64:65], v[50:51], off offset:96
	global_store_dwordx2 v[64:65], v[46:47], off offset:128
	global_store_dwordx2 v[64:65], v[38:39], off offset:192
	global_store_dwordx2 v[64:65], v[34:35], off offset:224
	global_store_dwordx2 v[64:65], v[28:29], off offset:256
	global_store_dwordx2 v[64:65], v[24:25], off offset:288
	global_store_dwordx2 v[64:65], v[20:21], off offset:320
	global_store_dwordx2 v[64:65], v[16:17], off offset:352
	global_store_dwordx2 v[64:65], v[12:13], off offset:384
	global_store_dwordx2 v[64:65], v[8:9], off offset:416
	global_store_dwordx2 v[64:65], v[4:5], off offset:448
	global_store_dwordx2 v[64:65], v[0:1], off offset:480
	s_cbranch_scc0 .LBB0_2087

; __device__ __forceinline__ uint2 pack4(float a, float b, float c, float d) { uint2 r; r.x = pk2(a, b); r.y = pk2(c, d); return r; }
; template <int NC, int DQK, int DV, bool CAUSAL, bool PF> ...
;     ...
;         float cc = bb - mrun[c];
;         _Pragma("unroll") for (int m = 0; m < 4; ++m) _Pragma("unroll") for (int j = 0; j < 4; ++j) { float pv = __builtin_amdgcn_exp2f(s[m][j] * scale_log2 + cc); s[m][j] = pv; psum += pv; }
;       }
;       lsum[c] += psum;
;       _Pragma("unroll") for (int k2 = 0; k2 < 2; ++k2) {
;         uint2 lo = pack4(s[2 * k2][0], s[2 * k2][1], s[2 * k2][2], s[2 * k2][3]);
;         uint2 hi = pack4(s[2 * k2 + 1][0], s[2 * k2 + 1][1], s[2 * k2 + 1][2], s[2 * k2 + 1][3]);
;         uint4 pk; pk.x = lo.x; pk.y = lo.y; pk.z = hi.x; pk.w = hi.y;
;         pf[c][k2] = *(bf16x8*)&pk;
;       }
;     }
;     _Pragma("unroll") for (int k2 = 0; k2 < 2; ++k2) _Pragma("unroll") for (int v = 0; v < NVT; ++v) {
;       bf16x8 a = *(const bf16x8*)&Vb[(16 * v + fr) * VLD + 32 * k2 + fq * 8];
;       _Pragma("unroll") for (int c = 0; c < NC; ++c) O[c][v] = __builtin_amdgcn_mfma_f32_16x16x32_bf16(a, pf[c][k2], O[c][v], 0, 0, 0);
;       if ((v & 3) == 3) __builtin_amdgcn_sched_barrier(0);
;     }
.LBB0_2082:
	v_sub_f32_e32 v191, 0, v152
	v_fmamk_f32 v142, v142, 0x3db8aa3b, v191
	v_exp_f32_e32 v142, v142
	v_fmamk_f32 v143, v143, 0x3db8aa3b, v191
	v_exp_f32_e32 v143, v143
	v_fmamk_f32 v144, v144, 0x3db8aa3b, v191
	v_exp_f32_e32 v144, v144
	v_fmamk_f32 v145, v145, 0x3db8aa3b, v191
	v_exp_f32_e32 v145, v145
	v_fmamk_f32 v138, v138, 0x3db8aa3b, v191
	v_add_f32_e32 v176, 0, v142
	v_exp_f32_e32 v138, v138
	v_fmamk_f32 v139, v139, 0x3db8aa3b, v191
	v_add_f32_e32 v176, v143, v176
	v_exp_f32_e32 v139, v139
	v_fmamk_f32 v140, v140, 0x3db8aa3b, v191
	v_add_f32_e32 v176, v144, v176
	v_exp_f32_e32 v140, v140
	v_fmamk_f32 v141, v141, 0x3db8aa3b, v191
	v_add_f32_e32 v176, v145, v176
	v_exp_f32_e32 v141, v141
	v_fmamk_f32 v134, v134, 0x3db8aa3b, v191
	v_add_f32_e32 v176, v138, v176
	v_exp_f32_e32 v177, v134
	v_add_f32_e32 v176, v139, v176
	v_add_f32_e32 v176, v140, v176
	v_add_f32_e32 v176, v141, v176
	v_fmamk_f32 v135, v135, 0x3db8aa3b, v191
	v_add_f32_e32 v134, v177, v176
	v_exp_f32_e32 v176, v135
	v_fmamk_f32 v135, v136, 0x3db8aa3b, v191
	v_exp_f32_e32 v192, v135
	v_fmamk_f32 v135, v137, 0x3db8aa3b, v191
	v_exp_f32_e32 v193, v135
	v_fmamk_f32 v130, v130, 0x3db8aa3b, v191
	v_exp_f32_e32 v194, v130
	v_add_f32_e32 v134, v176, v134
	v_add_f32_e32 v134, v192, v134
	v_add_f32_e32 v134, v193, v134
	v_add_f32_e32 v130, v194, v134
	v_cvt_pk_bf16_f32 v134, v142, v143
	v_add3_u32 v142, s23, v32, v151
	v_cvt_pk_bf16_f32 v136, v138, v139
	v_cvt_pk_bf16_f32 v137, v140, v141
	ds_read_b128 v[216:219], v142
	ds_read_b128 v[220:223], v142 offset:2304
	ds_read_b128 v[224:227], v142 offset:4608
	ds_read_b128 v[228:231], v142 offset:6912
	ds_read_b128 v[232:235], v142 offset:9216
	ds_read_b128 v[236:239], v142 offset:11520
	ds_read_b128 v[240:243], v142 offset:13824
	ds_read_b128 v[244:247], v142 offset:16128
	v_cvt_pk_bf16_f32 v135, v144, v145
	v_fmamk_f32 v131, v131, 0x3db8aa3b, v191
	v_exp_f32_e32 v195, v131
	s_waitcnt lgkmcnt(7)
	v_mfma_f32_16x16x32_bf16 v[62:65], v[216:219], v[134:137], v[62:65]
	ds_read_b128 v[216:219], v142 offset:18432
	v_fmamk_f32 v131, v132, 0x3db8aa3b, v191
	v_exp_f32_e32 v196, v131
	s_waitcnt lgkmcnt(7)
	v_mfma_f32_16x16x32_bf16 v[58:61], v[220:223], v[134:137], v[58:61]
	ds_read_b128 v[220:223], v142 offset:20736
	v_fmamk_f32 v131, v133, 0x3db8aa3b, v191
	v_exp_f32_e32 v133, v131
	s_waitcnt lgkmcnt(7)
	v_mfma_f32_16x16x32_bf16 v[54:57], v[224:227], v[134:137], v[54:57]
	ds_read_b128 v[224:227], v142 offset:23040
	v_add_f32_e32 v130, v195, v130
	v_add_f32_e32 v130, v196, v130
	s_waitcnt lgkmcnt(7)
	v_mfma_f32_16x16x32_bf16 v[50:53], v[228:231], v[134:137], v[50:53]
	ds_read_b128 v[228:231], v142 offset:25344
	v_add_f32_e32 v197, v133, v130
	v_cvt_pk_bf16_f32 v130, v177, v176
	v_cvt_pk_bf16_f32 v131, v192, v193
	v_cvt_pk_bf16_f32 v132, v194, v195
	v_cvt_pk_bf16_f32 v133, v196, v133
	s_waitcnt lgkmcnt(7)
	v_mfma_f32_16x16x32_bf16 v[46:49], v[232:235], v[134:137], v[46:49]
	ds_read_b128 v[232:235], v142 offset:27648
	s_waitcnt lgkmcnt(7)
	v_mfma_f32_16x16x32_bf16 v[38:41], v[236:239], v[134:137], v[38:41]
	ds_read_b128 v[236:239], v142 offset:29952
	s_waitcnt lgkmcnt(7)
	v_mfma_f32_16x16x32_bf16 v[42:45], v[240:243], v[134:137], v[42:45]
	ds_read_b128 v[240:243], v142 offset:32256
	s_waitcnt lgkmcnt(7)
	v_mfma_f32_16x16x32_bf16 v[34:37], v[244:247], v[134:137], v[34:37]
	ds_read_b128 v[244:247], v142 offset:34560
	s_waitcnt lgkmcnt(7)
	v_mfma_f32_16x16x32_bf16 v[28:31], v[216:219], v[134:137], v[28:31]
	s_waitcnt lgkmcnt(6)
	v_mfma_f32_16x16x32_bf16 v[24:27], v[220:223], v[134:137], v[24:27]
	s_waitcnt lgkmcnt(5)
	v_mfma_f32_16x16x32_bf16 v[20:23], v[224:227], v[134:137], v[20:23]
	s_waitcnt lgkmcnt(4)
	v_mfma_f32_16x16x32_bf16 v[16:19], v[228:231], v[134:137], v[16:19]
	s_waitcnt lgkmcnt(3)
	v_mfma_f32_16x16x32_bf16 v[12:15], v[232:235], v[134:137], v[12:15]
	s_waitcnt lgkmcnt(2)
	v_mfma_f32_16x16x32_bf16 v[8:11], v[236:239], v[134:137], v[8:11]
	s_waitcnt lgkmcnt(1)
	v_mfma_f32_16x16x32_bf16 v[4:7], v[240:243], v[134:137], v[4:7]
	s_waitcnt lgkmcnt(0)
	v_mfma_f32_16x16x32_bf16 v[0:3], v[244:247], v[134:137], v[0:3]
	ds_read_b128 v[216:219], v142 offset:64
	ds_read_b128 v[220:223], v142 offset:2368
	ds_read_b128 v[224:227], v142 offset:4672
	ds_read_b128 v[228:231], v142 offset:6976
	ds_read_b128 v[232:235], v142 offset:9280
	ds_read_b128 v[236:239], v142 offset:11584
	ds_read_b128 v[240:243], v142 offset:13888
	ds_read_b128 v[244:247], v142 offset:16192
	s_waitcnt lgkmcnt(7)
	v_mfma_f32_16x16x32_bf16 v[62:65], v[216:219], v[130:133], v[62:65]
	ds_read_b128 v[216:219], v142 offset:18496
	s_waitcnt lgkmcnt(7)
	v_mfma_f32_16x16x32_bf16 v[58:61], v[220:223], v[130:133], v[58:61]
	ds_read_b128 v[220:223], v142 offset:20800
	s_waitcnt lgkmcnt(7)
	v_mfma_f32_16x16x32_bf16 v[54:57], v[224:227], v[130:133], v[54:57]
	ds_read_b128 v[224:227], v142 offset:23104
	s_waitcnt lgkmcnt(7)
	v_mfma_f32_16x16x32_bf16 v[50:53], v[228:231], v[130:133], v[50:53]
	ds_read_b128 v[228:231], v142 offset:25408
	s_waitcnt lgkmcnt(7)
	v_mfma_f32_16x16x32_bf16 v[46:49], v[232:235], v[130:133], v[46:49]
	ds_read_b128 v[232:235], v142 offset:27712
	s_waitcnt lgkmcnt(7)
	v_mfma_f32_16x16x32_bf16 v[38:41], v[236:239], v[130:133], v[38:41]
	ds_read_b128 v[236:239], v142 offset:30016
	s_waitcnt lgkmcnt(7)
	v_mfma_f32_16x16x32_bf16 v[42:45], v[240:243], v[130:133], v[42:45]
	ds_read_b128 v[240:243], v142 offset:32320
	s_waitcnt lgkmcnt(7)
	v_mfma_f32_16x16x32_bf16 v[34:37], v[244:247], v[130:133], v[34:37]
	ds_read_b128 v[244:247], v142 offset:34624
	s_waitcnt lgkmcnt(7)
	v_mfma_f32_16x16x32_bf16 v[28:31], v[216:219], v[130:133], v[28:31]
	s_waitcnt lgkmcnt(6)
	v_mfma_f32_16x16x32_bf16 v[24:27], v[220:223], v[130:133], v[24:27]
	s_waitcnt lgkmcnt(5)
	v_mfma_f32_16x16x32_bf16 v[20:23], v[224:227], v[130:133], v[20:23]
	s_waitcnt lgkmcnt(4)
	v_mfma_f32_16x16x32_bf16 v[16:19], v[228:231], v[130:133], v[16:19]
	s_waitcnt lgkmcnt(3)
	v_mfma_f32_16x16x32_bf16 v[12:15], v[232:235], v[130:133], v[12:15]
	s_waitcnt lgkmcnt(2)
	v_mfma_f32_16x16x32_bf16 v[8:11], v[236:239], v[130:133], v[8:11]
	s_waitcnt lgkmcnt(1)
	v_mfma_f32_16x16x32_bf16 v[4:7], v[240:243], v[130:133], v[4:7]
	s_waitcnt lgkmcnt(0)
	v_mfma_f32_16x16x32_bf16 v[0:3], v[244:247], v[130:133], v[0:3]
	s_add_i32 s22, s22, 0x20000
	s_addk_i32 s21, 0x80
	s_add_i32 s20, s20, 1
	s_cmp_lg_u32 s22, 0x80000
	v_add_f32_e32 v150, v150, v197
	s_cbranch_scc0 .LBB0_2085
